# FFN-down halo patch pre-pass: the thread's three items per unit issue their loads together (one round trip per unit instead of three)
# speedup vs baseline: 1.0073x; 1.0073x over previous
; __global__ void __launch_bounds__(NTHREADS) mega_fwd(Params p) {
;     ...
;                 const float* ZS = (const float*)(AR + 176 * MiB); bf16_t* A2 = (bf16_t*)AR; const float* cw = p.in[31] + (size_t)fl * 3 * 5632; const float* cb = p.in[32] + (size_t)fl * 5632;
;                 pg8::Unit uu;
;                 for (int i = 0; S.next(i, uu); ++i) { if ((uu.pm & 15) == 0) continue;
;                     for (int idx = tid; idx < 2 * 704; idx += NTHREADS) { const int r = idx / 704, c = (idx - r * 704) * 4;
;                         f32x4 gsum = *(const f32x4*)(cb + c), vsum = *(const f32x4*)(cb + FFW + c);
; #pragma unroll
;                         for (int k = 0; k < 3; ++k) { const int j = r - 2 + k; const float* zr = (j < 0) ? ZS + ((size_t)(uu.pm - 1) * 4 + 4 + j) * 5632 : ZS + ((size_t)uu.pm * 4 + j) * 5632;
;                             gsum += *(const f32x4*)(cw + k * 5632 + c) * *(const f32x4*)(zr + c); vsum += *(const f32x4*)(cw + k * 5632 + FFW + c) * *(const f32x4*)(zr + FFW + c); }
.LBB0_260:
	s_waitcnt vmcnt(0)
	v_mov_b64_e32 v[2:3], 0x200
	v_cmp_lt_i64_e32 vcc, s[36:37], v[2:3]
	s_mov_b64 s[0:1], -1
	s_cbranch_vccz .LBB0_253
	s_and_b32 s0, s8, 15
	s_cmp_lg_u32 s0, 0
	s_cselect_b64 s[0:1], -1, 0
	s_and_b64 s[0:1], s[0:1], s[34:35]
	s_and_saveexec_b64 s[36:37], s[0:1]
	s_cbranch_execz .LBB0_252
	s_ashr_i32 s9, s8, 31
	s_lshl_b64 s[38:39], s[8:9], 2
	s_lshl_b32 s9, s8, 8
	s_mov_b64 s[40:41], 0
	v_mov_b32_e32 v50, v251
	v_add_u32_e32 v130, 0x200, v251
	v_add_u32_e32 v210, 0x400, v251
	v_mov_b32_e32 v81, 0
	v_mov_b32_e32 v161, 0
	s_mov_b32 s0, 0x2e8ba2e9
	v_mul_hi_i32 v0, v50, s0
	v_lshrrev_b32_e32 v2, 31, v0
	v_ashrrev_i32_e32 v0, 7, v0
	v_add_u32_e32 v44, v0, v2
	v_add_u32_e32 v10, -2, v44
	v_mul_i32_i24_e32 v0, 0xfffffd40, v44
	v_ashrrev_i32_e32 v11, 31, v10
	v_add_lshl_u32 v42, v0, v50, 2
	v_lshl_add_u64 v[10:11], s[38:39], 0, v[10:11]
	v_mov_b64_e32 v[12:13], s[4:5]
	v_ashrrev_i32_e32 v43, 31, v42
	v_mad_u64_u32 v[14:15], s[0:1], v10, s76, v[12:13]
	v_lshlrev_b64 v[46:47], 2, v[42:43]
	v_mad_i32_i24 v15, v11, s76, v15
	v_lshl_add_u64 v[2:3], s[18:19], 0, v[46:47]
	v_lshl_add_u64 v[4:5], s[20:21], 0, v[46:47]
	v_lshl_add_u64 v[22:23], v[14:15], 0, v[46:47]
	global_load_dwordx4 v[6:9], v[2:3], off
	s_nop 0
	global_load_dwordx4 v[2:5], v[4:5], off
	v_lshl_add_u64 v[10:11], s[16:17], 0, v[46:47]
	global_load_dwordx4 v[14:17], v[22:23], off
	v_add_co_u32_e32 v22, vcc, 0x2000, v22
	v_lshl_add_u64 v[18:19], s[22:23], 0, v[46:47]
	s_nop 0
	v_addc_co_u32_e32 v23, vcc, 0, v23, vcc
	global_load_dwordx4 v[10:13], v[10:11], off
	s_movk_i32 s0, 0x2bf
	global_load_dwordx4 v[18:21], v[18:19], off
	v_add_u32_e32 v0, -1, v44
	global_load_dwordx4 v[22:25], v[22:23], off offset:3072
	v_cmp_lt_i32_e32 vcc, s0, v50
	s_and_saveexec_b64 s[0:1], vcc
	s_xor_b64 s[0:1], exec, s[0:1]
	v_lshl_add_u64 v[26:27], s[38:39], 0, v[0:1]
	s_andn2_saveexec_b64 s[0:1], s[0:1]
	v_ashrrev_i32_e32 v27, 31, v0
	v_mov_b32_e32 v26, v0
	v_lshl_add_u64 v[26:27], s[38:39], 0, v[26:27]
	s_or_b64 exec, exec, s[0:1]
	v_mov_b64_e32 v[28:29], s[4:5]
	v_mad_u64_u32 v[30:31], s[0:1], v26, s76, v[28:29]
	v_mov_b32_e32 v0, v31
	v_mad_u64_u32 v[26:27], s[0:1], v27, s76, v[0:1]
	v_mov_b32_e32 v31, v26
	v_lshl_add_u64 v[38:39], v[30:31], 0, v[46:47]
	global_load_dwordx4 v[30:33], v[38:39], off
	v_add_co_u32_e32 v38, vcc, 0x2000, v38
	v_lshl_add_u64 v[26:27], s[24:25], 0, v[46:47]
	v_lshl_add_u64 v[34:35], s[26:27], 0, v[46:47]
	v_addc_co_u32_e32 v39, vcc, 0, v39, vcc
	global_load_dwordx4 v[26:29], v[26:27], off
	s_movk_i32 s0, 0xfd40
	global_load_dwordx4 v[34:37], v[34:35], off
	v_cmp_lt_i32_e32 vcc, s0, v50
	global_load_dwordx4 v[38:41], v[38:39], off offset:3072
	s_and_saveexec_b64 s[0:1], vcc
	s_xor_b64 s[0:1], exec, s[0:1]
	v_mov_b32_e32 v45, v1
	v_lshl_add_u64 v[48:49], s[38:39], 0, v[44:45]
	s_andn2_saveexec_b64 s[0:1], s[0:1]
	v_ashrrev_i32_e32 v45, 31, v44
	v_lshl_add_u64 v[48:49], s[38:39], 0, v[44:45]
	s_or_b64 exec, exec, s[0:1]
	v_mov_b64_e32 v[52:53], s[4:5]
	v_mad_u64_u32 v[54:55], s[0:1], v48, s76, v[52:53]
	v_mov_b32_e32 v0, v55
	v_mad_u64_u32 v[52:53], s[0:1], v49, s76, v[0:1]
	v_mov_b32_e32 v55, v52
	v_lshl_add_u64 v[56:57], s[28:29], 0, v[46:47]
	v_lshl_add_u64 v[54:55], v[54:55], 0, v[46:47]
	global_load_dwordx4 v[60:63], v[56:57], off
	v_add_co_u32_e32 v52, vcc, s63, v54
	v_lshl_add_u64 v[56:57], s[30:31], 0, v[46:47]
	global_load_dwordx4 v[64:67], v[54:55], off
	v_addc_co_u32_e32 v53, vcc, 0, v55, vcc
	global_load_dwordx4 v[68:71], v[56:57], off
	global_load_dwordx4 v[72:75], v[52:53], off offset:3072
	s_mov_b32 s0, 0x2e8ba2e9
	v_mul_hi_i32 v80, v130, s0
	v_lshrrev_b32_e32 v82, 31, v80
	v_ashrrev_i32_e32 v80, 7, v80
	v_add_u32_e32 v124, v80, v82
	v_add_u32_e32 v90, -2, v124
	v_mul_i32_i24_e32 v80, 0xfffffd40, v124
	v_ashrrev_i32_e32 v91, 31, v90
	v_add_lshl_u32 v122, v80, v130, 2
	v_lshl_add_u64 v[90:91], s[38:39], 0, v[90:91]
	v_mov_b64_e32 v[92:93], s[4:5]
	v_ashrrev_i32_e32 v123, 31, v122
	v_mad_u64_u32 v[94:95], s[0:1], v90, s76, v[92:93]
	v_lshlrev_b64 v[126:127], 2, v[122:123]
	v_mad_i32_i24 v95, v91, s76, v95
	v_lshl_add_u64 v[82:83], s[18:19], 0, v[126:127]
	v_lshl_add_u64 v[84:85], s[20:21], 0, v[126:127]
	v_lshl_add_u64 v[102:103], v[94:95], 0, v[126:127]
	global_load_dwordx4 v[86:89], v[82:83], off
	s_nop 0
	global_load_dwordx4 v[82:85], v[84:85], off
	v_lshl_add_u64 v[90:91], s[16:17], 0, v[126:127]
	global_load_dwordx4 v[94:97], v[102:103], off
	v_add_co_u32_e32 v102, vcc, 0x2000, v102
	v_lshl_add_u64 v[98:99], s[22:23], 0, v[126:127]
	s_nop 0
	v_addc_co_u32_e32 v103, vcc, 0, v103, vcc
	global_load_dwordx4 v[90:93], v[90:91], off
	s_movk_i32 s0, 0x2bf
	global_load_dwordx4 v[98:101], v[98:99], off
	v_add_u32_e32 v80, -1, v124
	global_load_dwordx4 v[102:105], v[102:103], off offset:3072
	v_cmp_lt_i32_e32 vcc, s0, v130
	s_and_saveexec_b64 s[0:1], vcc
	s_xor_b64 s[0:1], exec, s[0:1]
	v_lshl_add_u64 v[106:107], s[38:39], 0, v[80:81]
	s_andn2_saveexec_b64 s[0:1], s[0:1]
	v_ashrrev_i32_e32 v107, 31, v80
	v_mov_b32_e32 v106, v80
	v_lshl_add_u64 v[106:107], s[38:39], 0, v[106:107]
	s_or_b64 exec, exec, s[0:1]
	v_mov_b64_e32 v[108:109], s[4:5]
	v_mad_u64_u32 v[110:111], s[0:1], v106, s76, v[108:109]
	v_mov_b32_e32 v80, v111
	v_mad_u64_u32 v[106:107], s[0:1], v107, s76, v[80:81]
	v_mov_b32_e32 v111, v106
	v_lshl_add_u64 v[118:119], v[110:111], 0, v[126:127]
	global_load_dwordx4 v[110:113], v[118:119], off
	v_add_co_u32_e32 v118, vcc, 0x2000, v118
	v_lshl_add_u64 v[106:107], s[24:25], 0, v[126:127]
	v_lshl_add_u64 v[114:115], s[26:27], 0, v[126:127]
	v_addc_co_u32_e32 v119, vcc, 0, v119, vcc
	global_load_dwordx4 v[106:109], v[106:107], off
	s_movk_i32 s0, 0xfd40
	global_load_dwordx4 v[114:117], v[114:115], off
	v_cmp_lt_i32_e32 vcc, s0, v130
	global_load_dwordx4 v[118:121], v[118:119], off offset:3072
	s_and_saveexec_b64 s[0:1], vcc
	s_xor_b64 s[0:1], exec, s[0:1]
	v_mov_b32_e32 v125, v1
	v_lshl_add_u64 v[128:129], s[38:39], 0, v[124:125]
	s_andn2_saveexec_b64 s[0:1], s[0:1]
	v_ashrrev_i32_e32 v125, 31, v124
	v_lshl_add_u64 v[128:129], s[38:39], 0, v[124:125]
	s_or_b64 exec, exec, s[0:1]
	v_mov_b64_e32 v[132:133], s[4:5]
	v_mad_u64_u32 v[134:135], s[0:1], v128, s76, v[132:133]
	v_mov_b32_e32 v80, v135
	v_mad_u64_u32 v[132:133], s[0:1], v129, s76, v[80:81]
	v_mov_b32_e32 v135, v132
	v_lshl_add_u64 v[136:137], s[28:29], 0, v[126:127]
	v_lshl_add_u64 v[134:135], v[134:135], 0, v[126:127]
	global_load_dwordx4 v[140:143], v[136:137], off
	v_add_co_u32_e32 v132, vcc, s63, v134
	v_lshl_add_u64 v[136:137], s[30:31], 0, v[126:127]
	global_load_dwordx4 v[144:147], v[134:135], off
	v_addc_co_u32_e32 v133, vcc, 0, v135, vcc
	global_load_dwordx4 v[148:151], v[136:137], off
	global_load_dwordx4 v[152:155], v[132:133], off offset:3072
	v_cmp_gt_i32_e32 vcc, 0x580, v210
	s_and_saveexec_b64 s[40:41], vcc
	s_cbranch_execz .Lpatch_l2
; __device__ __forceinline__ unsigned cvt_pk_bf16(float lo, float hi) { unsigned r; asm("v_cvt_pk_bf16_f32 %0, %1, %2" : "=v"(r) : "v"(lo), "v"(hi)); return r; }
; __device__ __forceinline__ float siluf_(float x) { return x * sigmoidf_(x); }
; __device__ __forceinline__ float sigmoidf_(float x) { return 1.0f / (1.0f + __expf(-x)); }
; __global__ void __launch_bounds__(NTHREADS) mega_fwd(Params p) {
;     ...
;                     for (int idx = tid; idx < 2 * 704; idx += NTHREADS) { const int r = idx / 704, c = (idx - r * 704) * 4;
;                         f32x4 gsum = *(const f32x4*)(cb + c), vsum = *(const f32x4*)(cb + FFW + c);
; #pragma unroll
;                         for (int k = 0; k < 3; ++k) { const int j = r - 2 + k; const float* zr = (j < 0) ? ZS + ((size_t)(uu.pm - 1) * 4 + 4 + j) * 5632 : ZS + ((size_t)uu.pm * 4 + j) * 5632;
;                             gsum += *(const f32x4*)(cw + k * 5632 + c) * *(const f32x4*)(zr + c); vsum += *(const f32x4*)(cw + k * 5632 + FFW + c) * *(const f32x4*)(zr + FFW + c); }
;                         u32x2 w; w.x = cvt_pk_bf16(siluf_(gsum[0]) * vsum[0], siluf_(gsum[1]) * vsum[1]); w.y = cvt_pk_bf16(siluf_(gsum[2]) * vsum[2], siluf_(gsum[3]) * vsum[3]);
;                         *(u32x2*)(A2 + (size_t)(uu.pm * 256 + r) * FFW + c) = w; } }
	s_mov_b32 s0, 0x2e8ba2e9
	v_mul_hi_i32 v160, v210, s0
	v_lshrrev_b32_e32 v162, 31, v160
	v_ashrrev_i32_e32 v160, 7, v160
	v_add_u32_e32 v204, v160, v162
	v_add_u32_e32 v170, -2, v204
	v_mul_i32_i24_e32 v160, 0xfffffd40, v204
	v_ashrrev_i32_e32 v171, 31, v170
	v_add_lshl_u32 v202, v160, v210, 2
	v_lshl_add_u64 v[170:171], s[38:39], 0, v[170:171]
	v_mov_b64_e32 v[172:173], s[4:5]
	v_ashrrev_i32_e32 v203, 31, v202
	v_mad_u64_u32 v[174:175], s[0:1], v170, s76, v[172:173]
	v_lshlrev_b64 v[206:207], 2, v[202:203]
	v_mad_i32_i24 v175, v171, s76, v175
	v_lshl_add_u64 v[162:163], s[18:19], 0, v[206:207]
	v_lshl_add_u64 v[164:165], s[20:21], 0, v[206:207]
	v_lshl_add_u64 v[182:183], v[174:175], 0, v[206:207]
	global_load_dwordx4 v[166:169], v[162:163], off
	s_nop 0
	global_load_dwordx4 v[162:165], v[164:165], off
	v_lshl_add_u64 v[170:171], s[16:17], 0, v[206:207]
	global_load_dwordx4 v[174:177], v[182:183], off
	v_add_co_u32_e32 v182, vcc, 0x2000, v182
	v_lshl_add_u64 v[178:179], s[22:23], 0, v[206:207]
	s_nop 0
	v_addc_co_u32_e32 v183, vcc, 0, v183, vcc
	global_load_dwordx4 v[170:173], v[170:171], off
	s_movk_i32 s0, 0x2bf
	global_load_dwordx4 v[178:181], v[178:179], off
	v_add_u32_e32 v160, -1, v204
	global_load_dwordx4 v[182:185], v[182:183], off offset:3072
	v_cmp_lt_i32_e32 vcc, s0, v210
	s_and_saveexec_b64 s[0:1], vcc
	s_xor_b64 s[0:1], exec, s[0:1]
	v_lshl_add_u64 v[186:187], s[38:39], 0, v[160:161]
	s_andn2_saveexec_b64 s[0:1], s[0:1]
	v_ashrrev_i32_e32 v187, 31, v160
	v_mov_b32_e32 v186, v160
	v_lshl_add_u64 v[186:187], s[38:39], 0, v[186:187]
	s_or_b64 exec, exec, s[0:1]
	v_mov_b64_e32 v[188:189], s[4:5]
	v_mad_u64_u32 v[190:191], s[0:1], v186, s76, v[188:189]
	v_mov_b32_e32 v160, v191
	v_mad_u64_u32 v[186:187], s[0:1], v187, s76, v[160:161]
	v_mov_b32_e32 v191, v186
	v_lshl_add_u64 v[198:199], v[190:191], 0, v[206:207]
	global_load_dwordx4 v[190:193], v[198:199], off
	v_add_co_u32_e32 v198, vcc, 0x2000, v198
	v_lshl_add_u64 v[186:187], s[24:25], 0, v[206:207]
	v_lshl_add_u64 v[194:195], s[26:27], 0, v[206:207]
	v_addc_co_u32_e32 v199, vcc, 0, v199, vcc
	global_load_dwordx4 v[186:189], v[186:187], off
	s_movk_i32 s0, 0xfd40
	global_load_dwordx4 v[194:197], v[194:195], off
	v_cmp_lt_i32_e32 vcc, s0, v210
	global_load_dwordx4 v[198:201], v[198:199], off offset:3072
	s_and_saveexec_b64 s[0:1], vcc
	s_xor_b64 s[0:1], exec, s[0:1]
	v_mov_b32_e32 v205, v1
	v_lshl_add_u64 v[208:209], s[38:39], 0, v[204:205]
	s_andn2_saveexec_b64 s[0:1], s[0:1]
	v_ashrrev_i32_e32 v205, 31, v204
	v_lshl_add_u64 v[208:209], s[38:39], 0, v[204:205]
	s_or_b64 exec, exec, s[0:1]
	v_mov_b64_e32 v[212:213], s[4:5]
	v_mad_u64_u32 v[214:215], s[0:1], v208, s76, v[212:213]
	v_mov_b32_e32 v160, v215
	v_mad_u64_u32 v[212:213], s[0:1], v209, s76, v[160:161]
	v_mov_b32_e32 v215, v212
	v_lshl_add_u64 v[216:217], s[28:29], 0, v[206:207]
	v_lshl_add_u64 v[214:215], v[214:215], 0, v[206:207]
	global_load_dwordx4 v[220:223], v[216:217], off
	v_add_co_u32_e32 v212, vcc, s63, v214
	v_lshl_add_u64 v[216:217], s[30:31], 0, v[206:207]
	global_load_dwordx4 v[224:227], v[214:215], off
	v_addc_co_u32_e32 v213, vcc, 0, v215, vcc
	global_load_dwordx4 v[228:231], v[216:217], off
	global_load_dwordx4 v[232:235], v[212:213], off offset:3072
.Lpatch_l2:
	s_or_b64 exec, exec, s[40:41]
	s_waitcnt vmcnt(0) lgkmcnt(0)
	v_pk_fma_f32 v[2:3], v[18:19], v[22:23], v[2:3]
	v_pk_fma_f32 v[8:9], v[12:13], v[16:17], v[8:9]
	v_pk_fma_f32 v[6:7], v[10:11], v[14:15], v[6:7]
	v_pk_fma_f32 v[16:17], v[34:35], v[38:39], v[2:3]
	v_pk_fma_f32 v[12:13], v[26:27], v[30:31], v[6:7]
	v_pk_fma_f32 v[4:5], v[20:21], v[24:25], v[4:5]
	v_pk_fma_f32 v[10:11], v[28:29], v[32:33], v[8:9]
	v_pk_fma_f32 v[14:15], v[36:37], v[40:41], v[4:5]
	v_pk_fma_f32 v[12:13], v[60:61], v[64:65], v[12:13]
	v_pk_fma_f32 v[10:11], v[62:63], v[66:67], v[10:11]
	v_mul_f32_e32 v0, 0xbfb8aa3b, v12
	v_exp_f32_e32 v0, v0
	v_pk_fma_f32 v[2:3], v[68:69], v[72:73], v[16:17]
	v_add_f32_e32 v0, 1.0, v0
	v_div_scale_f32 v6, s[0:1], v0, v0, 1.0
	v_rcp_f32_e32 v7, v6
	v_pk_fma_f32 v[4:5], v[70:71], v[74:75], v[14:15]
	v_fma_f32 v8, -v6, v7, 1.0
	v_fmac_f32_e32 v7, v8, v7
	v_div_scale_f32 v8, vcc, 1.0, v0, 1.0
	v_mul_f32_e32 v9, v8, v7
	v_fma_f32 v14, -v6, v9, v8
	v_fmac_f32_e32 v9, v14, v7
	v_fma_f32 v6, -v6, v9, v8
	v_div_fmas_f32 v6, v6, v7, v9
	v_div_fixup_f32 v0, v6, v0, 1.0
	v_mul_f32_e32 v0, v12, v0
	v_mul_f32_e32 v0, v2, v0
	v_mul_f32_e32 v2, 0xbfb8aa3b, v13
	v_exp_f32_e32 v2, v2
	s_nop 0
	v_add_f32_e32 v2, 1.0, v2
	v_div_scale_f32 v6, s[0:1], v2, v2, 1.0
	v_rcp_f32_e32 v7, v6
	s_nop 0
	v_fma_f32 v8, -v6, v7, 1.0
	v_fmac_f32_e32 v7, v8, v7
	v_div_scale_f32 v8, vcc, 1.0, v2, 1.0
	v_mul_f32_e32 v9, v8, v7
	v_fma_f32 v12, -v6, v9, v8
	v_fmac_f32_e32 v9, v12, v7
	v_fma_f32 v6, -v6, v9, v8
	v_div_fmas_f32 v6, v6, v7, v9
	v_div_fixup_f32 v2, v6, v2, 1.0
	v_mul_f32_e32 v2, v13, v2
	v_mul_f32_e32 v2, v3, v2
	v_cvt_pk_bf16_f32 v2, v0, v2
	v_mul_f32_e32 v0, 0xbfb8aa3b, v10
	v_exp_f32_e32 v0, v0
	s_nop 0
	v_add_f32_e32 v0, 1.0, v0
	v_div_scale_f32 v3, s[0:1], v0, v0, 1.0
	v_rcp_f32_e32 v6, v3
	s_nop 0
	v_fma_f32 v7, -v3, v6, 1.0
	v_fmac_f32_e32 v6, v7, v6
	v_div_scale_f32 v7, vcc, 1.0, v0, 1.0
	v_mul_f32_e32 v8, v7, v6
	v_fma_f32 v9, -v3, v8, v7
	v_fmac_f32_e32 v8, v9, v6
	v_fma_f32 v3, -v3, v8, v7
	v_div_fmas_f32 v3, v3, v6, v8
	v_div_fixup_f32 v0, v3, v0, 1.0
	v_mul_f32_e32 v3, 0xbfb8aa3b, v11
	v_exp_f32_e32 v3, v3
	v_mul_f32_e32 v0, v10, v0
	v_mul_f32_e32 v0, v4, v0
	v_add_f32_e32 v3, 1.0, v3
	v_div_scale_f32 v4, s[0:1], v3, v3, 1.0
	v_rcp_f32_e32 v6, v4
	s_nop 0
	v_fma_f32 v7, -v4, v6, 1.0
	v_fmac_f32_e32 v6, v7, v6
	v_div_scale_f32 v7, vcc, 1.0, v3, 1.0
; __device__ __forceinline__ unsigned cvt_pk_bf16(float lo, float hi) { unsigned r; asm("v_cvt_pk_bf16_f32 %0, %1, %2" : "=v"(r) : "v"(lo), "v"(hi)); return r; }
; __device__ __forceinline__ float siluf_(float x) { return x * sigmoidf_(x); }
; __global__ void __launch_bounds__(NTHREADS) mega_fwd(Params p) {
;     ...
;                     for (int idx = tid; idx < 2 * 704; idx += NTHREADS) { const int r = idx / 704, c = (idx - r * 704) * 4;
;                         f32x4 gsum = *(const f32x4*)(cb + c), vsum = *(const f32x4*)(cb + FFW + c);
; #pragma unroll
;                         for (int k = 0; k < 3; ++k) { const int j = r - 2 + k; const float* zr = (j < 0) ? ZS + ((size_t)(uu.pm - 1) * 4 + 4 + j) * 5632 : ZS + ((size_t)uu.pm * 4 + j) * 5632;
;                             gsum += *(const f32x4*)(cw + k * 5632 + c) * *(const f32x4*)(zr + c); vsum += *(const f32x4*)(cw + k * 5632 + FFW + c) * *(const f32x4*)(zr + FFW + c); }
;                         u32x2 w; w.x = cvt_pk_bf16(siluf_(gsum[0]) * vsum[0], siluf_(gsum[1]) * vsum[1]); w.y = cvt_pk_bf16(siluf_(gsum[2]) * vsum[2], siluf_(gsum[3]) * vsum[3]);
;                         *(u32x2*)(A2 + (size_t)(uu.pm * 256 + r) * FFW + c) = w; } }
	v_mul_f32_e32 v8, v7, v6
	v_fma_f32 v9, -v4, v8, v7
	v_fmac_f32_e32 v8, v9, v6
	v_fma_f32 v4, -v4, v8, v7
	v_div_fmas_f32 v4, v4, v6, v8
	v_div_fixup_f32 v3, v4, v3, 1.0
	v_mul_f32_e32 v3, v11, v3
	v_mul_f32_e32 v3, v5, v3
	v_cvt_pk_bf16_f32 v3, v0, v3
	v_add_u32_e32 v0, s9, v44
	v_mov_b64_e32 v[4:5], s[70:71]
	v_mad_i64_i32 v[4:5], s[0:1], v0, s77, v[4:5]
	v_lshl_add_u64 v[4:5], v[42:43], 1, v[4:5]
	global_store_dwordx2 v[4:5], v[2:3], off
	v_pk_fma_f32 v[82:83], v[98:99], v[102:103], v[82:83]
	v_pk_fma_f32 v[88:89], v[92:93], v[96:97], v[88:89]
	v_pk_fma_f32 v[86:87], v[90:91], v[94:95], v[86:87]
	v_pk_fma_f32 v[96:97], v[114:115], v[118:119], v[82:83]
	v_pk_fma_f32 v[92:93], v[106:107], v[110:111], v[86:87]
	v_pk_fma_f32 v[84:85], v[100:101], v[104:105], v[84:85]
	v_pk_fma_f32 v[90:91], v[108:109], v[112:113], v[88:89]
	v_pk_fma_f32 v[94:95], v[116:117], v[120:121], v[84:85]
	v_pk_fma_f32 v[92:93], v[140:141], v[144:145], v[92:93]
	v_pk_fma_f32 v[90:91], v[142:143], v[146:147], v[90:91]
	v_mul_f32_e32 v80, 0xbfb8aa3b, v92
	v_exp_f32_e32 v80, v80
	v_pk_fma_f32 v[82:83], v[148:149], v[152:153], v[96:97]
	v_add_f32_e32 v80, 1.0, v80
	v_div_scale_f32 v86, s[0:1], v80, v80, 1.0
	v_rcp_f32_e32 v87, v86
	v_pk_fma_f32 v[84:85], v[150:151], v[154:155], v[94:95]
	v_fma_f32 v88, -v86, v87, 1.0
	v_fmac_f32_e32 v87, v88, v87
	v_div_scale_f32 v88, vcc, 1.0, v80, 1.0
	v_mul_f32_e32 v89, v88, v87
	v_fma_f32 v94, -v86, v89, v88
	v_fmac_f32_e32 v89, v94, v87
	v_fma_f32 v86, -v86, v89, v88
	v_div_fmas_f32 v86, v86, v87, v89
	v_div_fixup_f32 v80, v86, v80, 1.0
	v_mul_f32_e32 v80, v92, v80
	v_mul_f32_e32 v80, v82, v80
	v_mul_f32_e32 v82, 0xbfb8aa3b, v93
	v_exp_f32_e32 v82, v82
	s_nop 0
	v_add_f32_e32 v82, 1.0, v82
	v_div_scale_f32 v86, s[0:1], v82, v82, 1.0
	v_rcp_f32_e32 v87, v86
	s_nop 0
	v_fma_f32 v88, -v86, v87, 1.0
	v_fmac_f32_e32 v87, v88, v87
	v_div_scale_f32 v88, vcc, 1.0, v82, 1.0
	v_mul_f32_e32 v89, v88, v87
	v_fma_f32 v92, -v86, v89, v88
	v_fmac_f32_e32 v89, v92, v87
	v_fma_f32 v86, -v86, v89, v88
	v_div_fmas_f32 v86, v86, v87, v89
	v_div_fixup_f32 v82, v86, v82, 1.0
	v_mul_f32_e32 v82, v93, v82
	v_mul_f32_e32 v82, v83, v82
	v_cvt_pk_bf16_f32 v82, v80, v82
	v_mul_f32_e32 v80, 0xbfb8aa3b, v90
	v_exp_f32_e32 v80, v80
	s_nop 0
	v_add_f32_e32 v80, 1.0, v80
	v_div_scale_f32 v83, s[0:1], v80, v80, 1.0
	v_rcp_f32_e32 v86, v83
	s_nop 0
	v_fma_f32 v87, -v83, v86, 1.0
	v_fmac_f32_e32 v86, v87, v86
	v_div_scale_f32 v87, vcc, 1.0, v80, 1.0
	v_mul_f32_e32 v88, v87, v86
	v_fma_f32 v89, -v83, v88, v87
	v_fmac_f32_e32 v88, v89, v86
	v_fma_f32 v83, -v83, v88, v87
	v_div_fmas_f32 v83, v83, v86, v88
	v_div_fixup_f32 v80, v83, v80, 1.0
	v_mul_f32_e32 v83, 0xbfb8aa3b, v91
	v_exp_f32_e32 v83, v83
	v_mul_f32_e32 v80, v90, v80
	v_mul_f32_e32 v80, v84, v80
	v_add_f32_e32 v83, 1.0, v83
	v_div_scale_f32 v84, s[0:1], v83, v83, 1.0
	v_rcp_f32_e32 v86, v84
	s_nop 0
	v_fma_f32 v87, -v84, v86, 1.0
	v_fmac_f32_e32 v86, v87, v86
	v_div_scale_f32 v87, vcc, 1.0, v83, 1.0
	v_mul_f32_e32 v88, v87, v86
	v_fma_f32 v89, -v84, v88, v87
	v_fmac_f32_e32 v88, v89, v86
	v_fma_f32 v84, -v84, v88, v87
	v_div_fmas_f32 v84, v84, v86, v88
	v_div_fixup_f32 v83, v84, v83, 1.0
	v_mul_f32_e32 v83, v91, v83
	v_mul_f32_e32 v83, v85, v83
	v_cvt_pk_bf16_f32 v83, v80, v83
	v_add_u32_e32 v80, s9, v124
	v_mov_b64_e32 v[84:85], s[70:71]
	v_mad_i64_i32 v[84:85], s[0:1], v80, s77, v[84:85]
	v_lshl_add_u64 v[84:85], v[122:123], 1, v[84:85]
	global_store_dwordx2 v[84:85], v[82:83], off
	v_cmp_gt_i32_e32 vcc, 0x580, v210
	s_and_saveexec_b64 s[40:41], vcc
	s_cbranch_execz .Lpatch_c2
	v_pk_fma_f32 v[162:163], v[178:179], v[182:183], v[162:163]
	v_pk_fma_f32 v[168:169], v[172:173], v[176:177], v[168:169]
	v_pk_fma_f32 v[166:167], v[170:171], v[174:175], v[166:167]
	v_pk_fma_f32 v[176:177], v[194:195], v[198:199], v[162:163]
	v_pk_fma_f32 v[172:173], v[186:187], v[190:191], v[166:167]
	v_pk_fma_f32 v[164:165], v[180:181], v[184:185], v[164:165]
	v_pk_fma_f32 v[170:171], v[188:189], v[192:193], v[168:169]
	v_pk_fma_f32 v[174:175], v[196:197], v[200:201], v[164:165]
	v_pk_fma_f32 v[172:173], v[220:221], v[224:225], v[172:173]
	v_pk_fma_f32 v[170:171], v[222:223], v[226:227], v[170:171]
	v_mul_f32_e32 v160, 0xbfb8aa3b, v172
	v_exp_f32_e32 v160, v160
	v_pk_fma_f32 v[162:163], v[228:229], v[232:233], v[176:177]
	v_add_f32_e32 v160, 1.0, v160
	v_div_scale_f32 v166, s[0:1], v160, v160, 1.0
	v_rcp_f32_e32 v167, v166
	v_pk_fma_f32 v[164:165], v[230:231], v[234:235], v[174:175]
	v_fma_f32 v168, -v166, v167, 1.0
	v_fmac_f32_e32 v167, v168, v167
	v_div_scale_f32 v168, vcc, 1.0, v160, 1.0
	v_mul_f32_e32 v169, v168, v167
	v_fma_f32 v174, -v166, v169, v168
	v_fmac_f32_e32 v169, v174, v167
	v_fma_f32 v166, -v166, v169, v168
	v_div_fmas_f32 v166, v166, v167, v169
	v_div_fixup_f32 v160, v166, v160, 1.0
	v_mul_f32_e32 v160, v172, v160
	v_mul_f32_e32 v160, v162, v160
	v_mul_f32_e32 v162, 0xbfb8aa3b, v173
	v_exp_f32_e32 v162, v162
	s_nop 0
	v_add_f32_e32 v162, 1.0, v162
	v_div_scale_f32 v166, s[0:1], v162, v162, 1.0
	v_rcp_f32_e32 v167, v166
	s_nop 0
	v_fma_f32 v168, -v166, v167, 1.0
	v_fmac_f32_e32 v167, v168, v167
	v_div_scale_f32 v168, vcc, 1.0, v162, 1.0
	v_mul_f32_e32 v169, v168, v167
	v_fma_f32 v172, -v166, v169, v168
	v_fmac_f32_e32 v169, v172, v167
	v_fma_f32 v166, -v166, v169, v168
	v_div_fmas_f32 v166, v166, v167, v169
	v_div_fixup_f32 v162, v166, v162, 1.0
	v_mul_f32_e32 v162, v173, v162
	v_mul_f32_e32 v162, v163, v162
	v_cvt_pk_bf16_f32 v162, v160, v162
	v_mul_f32_e32 v160, 0xbfb8aa3b, v170
	v_exp_f32_e32 v160, v160
	s_nop 0
	v_add_f32_e32 v160, 1.0, v160
	v_div_scale_f32 v163, s[0:1], v160, v160, 1.0
	v_rcp_f32_e32 v166, v163
	s_nop 0
	v_fma_f32 v167, -v163, v166, 1.0
	v_fmac_f32_e32 v166, v167, v166
	v_div_scale_f32 v167, vcc, 1.0, v160, 1.0
	v_mul_f32_e32 v168, v167, v166
	v_fma_f32 v169, -v163, v168, v167
	v_fmac_f32_e32 v168, v169, v166
	v_fma_f32 v163, -v163, v168, v167
	v_div_fmas_f32 v163, v163, v166, v168
	v_div_fixup_f32 v160, v163, v160, 1.0
	v_mul_f32_e32 v163, 0xbfb8aa3b, v171
	v_exp_f32_e32 v163, v163
	v_mul_f32_e32 v160, v170, v160
	v_mul_f32_e32 v160, v164, v160
	v_add_f32_e32 v163, 1.0, v163
	v_div_scale_f32 v164, s[0:1], v163, v163, 1.0
	v_rcp_f32_e32 v166, v164
	s_nop 0
	v_fma_f32 v167, -v164, v166, 1.0
	v_fmac_f32_e32 v166, v167, v166
	v_div_scale_f32 v167, vcc, 1.0, v163, 1.0
	v_mul_f32_e32 v168, v167, v166
	v_fma_f32 v169, -v164, v168, v167
	v_fmac_f32_e32 v168, v169, v166
	v_fma_f32 v164, -v164, v168, v167
	v_div_fmas_f32 v164, v164, v166, v168
	v_div_fixup_f32 v163, v164, v163, 1.0
	v_mul_f32_e32 v163, v171, v163
	v_mul_f32_e32 v163, v165, v163
	v_cvt_pk_bf16_f32 v163, v160, v163
	v_add_u32_e32 v160, s9, v204
	v_mov_b64_e32 v[164:165], s[70:71]
	v_mad_i64_i32 v[164:165], s[0:1], v160, s77, v[164:165]
	v_lshl_add_u64 v[164:165], v[202:203], 1, v[164:165]
	global_store_dwordx2 v[164:165], v[162:163], off
.Lpatch_c2:
	s_or_b64 exec, exec, s[40:41]
	s_branch .LBB0_252
